# 2-deep register prefetch in gemm_down main loop + write-through (sc0 sc1) stores in the hand-written residual epilogues
# speedup vs baseline: 1.0540x; 1.0104x over previous
.Lgo_src_done:
	s_mul_i32 s12, s0, 0x12000
	s_add_u32 s12, s12, 0x2a22000
	s_sub_u32 s1, s40, 16
	s_lshr_b32 s1, s1, 4
	s_cmp_lt_u32 s40, 32
	s_cselect_b32 s1, 0, s1
	s_mul_i32 s1, s1, 0x6000
	s_add_u32 s12, s12, s1
	s_add_u32 s12, s12, s7
	s_add_u32 s12, s2, s12
	s_addc_u32 s13, s3, 0
	v_and_b32_e32 v64, 31, v231
	v_bfe_u32 v65, v231, 6, 1
	v_lshl_or_b32 v65, v65, 6, v64
	v_lshlrev_b32_e32 v65, 2, v65
	v_bfe_u32 v64, v231, 5, 1
	v_bfe_u32 v66, v231, 7, 1
	v_lshl_or_b32 v64, v66, 4, v64
	v_lshl_or_b32 v64, v64, 14, v65
	global_load_dword v66, v65, s[12:13]
	global_load_dword v67, v65, s[12:13] offset:128
	s_add_u32 s14, s10, 0x1000
	s_addc_u32 s15, s11, 0
	global_load_dword v68, v64, s[14:15] offset:-4096
	global_load_dword v69, v64, s[14:15] offset:-3968
	global_load_dword v70, v64, s[14:15]
	global_load_dword v71, v64, s[14:15] offset:128
	s_add_u32 s14, s10, 0x3000
	s_addc_u32 s15, s11, 0
	global_load_dword v72, v64, s[14:15] offset:-4096
	global_load_dword v73, v64, s[14:15] offset:-3968
	global_load_dword v74, v64, s[14:15]
	global_load_dword v75, v64, s[14:15] offset:128
	s_add_u32 s14, s10, 0x9000
	s_addc_u32 s15, s11, 0
	global_load_dword v76, v64, s[14:15] offset:-4096
	global_load_dword v77, v64, s[14:15] offset:-3968
	global_load_dword v78, v64, s[14:15]
	global_load_dword v79, v64, s[14:15] offset:128
	s_add_u32 s14, s10, 0xb000
	s_addc_u32 s15, s11, 0
	global_load_dword v80, v64, s[14:15] offset:-4096
	global_load_dword v81, v64, s[14:15] offset:-3968
	global_load_dword v82, v64, s[14:15]
	global_load_dword v83, v64, s[14:15] offset:128
	s_add_u32 s14, s10, 0x11000
	s_addc_u32 s15, s11, 0
	global_load_dword v84, v64, s[14:15] offset:-4096
	global_load_dword v85, v64, s[14:15] offset:-3968
	global_load_dword v86, v64, s[14:15]
	global_load_dword v87, v64, s[14:15] offset:128
	s_add_u32 s14, s10, 0x13000
	s_addc_u32 s15, s11, 0
	global_load_dword v88, v64, s[14:15] offset:-4096
	global_load_dword v89, v64, s[14:15] offset:-3968
	global_load_dword v90, v64, s[14:15]
	global_load_dword v91, v64, s[14:15] offset:128
	s_add_u32 s14, s10, 0x19000
	s_addc_u32 s15, s11, 0
	global_load_dword v92, v64, s[14:15] offset:-4096
	global_load_dword v93, v64, s[14:15] offset:-3968
	global_load_dword v94, v64, s[14:15]
	global_load_dword v95, v64, s[14:15] offset:128
	s_add_u32 s14, s10, 0x1b000
	s_addc_u32 s15, s11, 0
	global_load_dword v96, v64, s[14:15] offset:-4096
	global_load_dword v97, v64, s[14:15] offset:-3968
	global_load_dword v98, v64, s[14:15]
	global_load_dword v99, v64, s[14:15] offset:128
	s_add_u32 s14, s10, 0x21000
	s_addc_u32 s15, s11, 0
	global_load_dword v100, v64, s[14:15] offset:-4096
	global_load_dword v101, v64, s[14:15] offset:-3968
	global_load_dword v102, v64, s[14:15]
	global_load_dword v103, v64, s[14:15] offset:128
	s_add_u32 s14, s10, 0x23000
	s_addc_u32 s15, s11, 0
	global_load_dword v104, v64, s[14:15] offset:-4096
	global_load_dword v105, v64, s[14:15] offset:-3968
	global_load_dword v106, v64, s[14:15]
	global_load_dword v107, v64, s[14:15] offset:128
	s_add_u32 s14, s10, 0x29000
	s_addc_u32 s15, s11, 0
	global_load_dword v108, v64, s[14:15] offset:-4096
	global_load_dword v109, v64, s[14:15] offset:-3968
	global_load_dword v110, v64, s[14:15]
	global_load_dword v111, v64, s[14:15] offset:128
	s_add_u32 s14, s10, 0x2b000
	s_addc_u32 s15, s11, 0
	global_load_dword v112, v64, s[14:15] offset:-4096
	global_load_dword v113, v64, s[14:15] offset:-3968
	global_load_dword v114, v64, s[14:15]
	global_load_dword v115, v64, s[14:15] offset:128
	s_add_u32 s14, s10, 0x31000
	s_addc_u32 s15, s11, 0
	global_load_dword v116, v64, s[14:15] offset:-4096
	global_load_dword v117, v64, s[14:15] offset:-3968
	global_load_dword v118, v64, s[14:15]
	global_load_dword v119, v64, s[14:15] offset:128
	s_add_u32 s14, s10, 0x33000
	s_addc_u32 s15, s11, 0
	global_load_dword v120, v64, s[14:15] offset:-4096
	global_load_dword v121, v64, s[14:15] offset:-3968
	global_load_dword v122, v64, s[14:15]
	global_load_dword v123, v64, s[14:15] offset:128
	s_add_u32 s14, s10, 0x39000
	s_addc_u32 s15, s11, 0
	global_load_dword v124, v64, s[14:15] offset:-4096
	global_load_dword v125, v64, s[14:15] offset:-3968
	global_load_dword v126, v64, s[14:15]
	global_load_dword v127, v64, s[14:15] offset:128
	s_add_u32 s14, s10, 0x3b000
	s_addc_u32 s15, s11, 0
	global_load_dword v128, v64, s[14:15] offset:-4096
	global_load_dword v129, v64, s[14:15] offset:-3968
	global_load_dword v130, v64, s[14:15]
	global_load_dword v131, v64, s[14:15] offset:128
	s_waitcnt vmcnt(32)
	v_fmac_f32_e32 v68, v66, v48
	v_fmac_f32_e32 v69, v67, v32
	v_fmac_f32_e32 v70, v66, v49
	v_fmac_f32_e32 v71, v67, v33
	v_fmac_f32_e32 v72, v66, v50
	v_fmac_f32_e32 v73, v67, v34
	v_fmac_f32_e32 v74, v66, v51
	v_fmac_f32_e32 v75, v67, v35
	v_fmac_f32_e32 v76, v66, v52
	v_fmac_f32_e32 v77, v67, v36
	v_fmac_f32_e32 v78, v66, v53
	v_fmac_f32_e32 v79, v67, v37
	v_fmac_f32_e32 v80, v66, v54
	v_fmac_f32_e32 v81, v67, v38
	v_fmac_f32_e32 v82, v66, v55
	v_fmac_f32_e32 v83, v67, v39
	v_fmac_f32_e32 v84, v66, v56
	v_fmac_f32_e32 v85, v67, v40
	v_fmac_f32_e32 v86, v66, v57
	v_fmac_f32_e32 v87, v67, v41
	v_fmac_f32_e32 v88, v66, v58
	v_fmac_f32_e32 v89, v67, v42
	v_fmac_f32_e32 v90, v66, v59
	v_fmac_f32_e32 v91, v67, v43
	v_fmac_f32_e32 v92, v66, v60
	v_fmac_f32_e32 v93, v67, v44
	v_fmac_f32_e32 v94, v66, v61
	v_fmac_f32_e32 v95, v67, v45
	v_fmac_f32_e32 v96, v66, v62
	v_fmac_f32_e32 v97, v67, v46
	v_fmac_f32_e32 v98, v66, v63
	v_fmac_f32_e32 v99, v67, v47
	s_add_u32 s14, s8, 0x1000
	s_addc_u32 s15, s9, 0
	global_store_dword v64, v68, s[14:15] offset:-4096 sc0 sc1
	global_store_dword v64, v69, s[14:15] offset:-3968 sc0 sc1
	global_store_dword v64, v70, s[14:15] sc0 sc1
	global_store_dword v64, v71, s[14:15] offset:128 sc0 sc1
	s_add_u32 s14, s8, 0x3000
	s_addc_u32 s15, s9, 0
	global_store_dword v64, v72, s[14:15] offset:-4096 sc0 sc1
	global_store_dword v64, v73, s[14:15] offset:-3968 sc0 sc1
	global_store_dword v64, v74, s[14:15] sc0 sc1
	global_store_dword v64, v75, s[14:15] offset:128 sc0 sc1
	s_add_u32 s14, s8, 0x9000
	s_addc_u32 s15, s9, 0
	global_store_dword v64, v76, s[14:15] offset:-4096 sc0 sc1
	global_store_dword v64, v77, s[14:15] offset:-3968 sc0 sc1
	global_store_dword v64, v78, s[14:15] sc0 sc1
	global_store_dword v64, v79, s[14:15] offset:128 sc0 sc1
	s_add_u32 s14, s8, 0xb000
	s_addc_u32 s15, s9, 0
	global_store_dword v64, v80, s[14:15] offset:-4096 sc0 sc1
	global_store_dword v64, v81, s[14:15] offset:-3968 sc0 sc1
	global_store_dword v64, v82, s[14:15] sc0 sc1
	global_store_dword v64, v83, s[14:15] offset:128 sc0 sc1
	s_add_u32 s14, s8, 0x11000
	s_addc_u32 s15, s9, 0
	global_store_dword v64, v84, s[14:15] offset:-4096 sc0 sc1
	global_store_dword v64, v85, s[14:15] offset:-3968 sc0 sc1
	global_store_dword v64, v86, s[14:15] sc0 sc1
	global_store_dword v64, v87, s[14:15] offset:128 sc0 sc1
	s_add_u32 s14, s8, 0x13000
	s_addc_u32 s15, s9, 0
	global_store_dword v64, v88, s[14:15] offset:-4096 sc0 sc1
	global_store_dword v64, v89, s[14:15] offset:-3968 sc0 sc1
	global_store_dword v64, v90, s[14:15] sc0 sc1
	global_store_dword v64, v91, s[14:15] offset:128 sc0 sc1
	s_add_u32 s14, s8, 0x19000
	s_addc_u32 s15, s9, 0
	global_store_dword v64, v92, s[14:15] offset:-4096 sc0 sc1
	global_store_dword v64, v93, s[14:15] offset:-3968 sc0 sc1
	global_store_dword v64, v94, s[14:15] sc0 sc1
	global_store_dword v64, v95, s[14:15] offset:128 sc0 sc1
	s_add_u32 s14, s8, 0x1b000
	s_addc_u32 s15, s9, 0
	global_store_dword v64, v96, s[14:15] offset:-4096 sc0 sc1
	global_store_dword v64, v97, s[14:15] offset:-3968 sc0 sc1
	global_store_dword v64, v98, s[14:15] sc0 sc1
	global_store_dword v64, v99, s[14:15] offset:128 sc0 sc1
	s_waitcnt vmcnt(32)
	v_fmac_f32_e32 v100, v66, v16
	v_fmac_f32_e32 v101, v67, v0
	v_fmac_f32_e32 v102, v66, v17
	v_fmac_f32_e32 v103, v67, v1
	v_fmac_f32_e32 v104, v66, v18
	v_fmac_f32_e32 v105, v67, v2
	v_fmac_f32_e32 v106, v66, v19
	v_fmac_f32_e32 v107, v67, v3
	v_fmac_f32_e32 v108, v66, v20
	v_fmac_f32_e32 v109, v67, v4
	v_fmac_f32_e32 v110, v66, v21
	v_fmac_f32_e32 v111, v67, v5
	v_fmac_f32_e32 v112, v66, v22
	v_fmac_f32_e32 v113, v67, v6
	v_fmac_f32_e32 v114, v66, v23
	v_fmac_f32_e32 v115, v67, v7
	v_fmac_f32_e32 v116, v66, v24
	v_fmac_f32_e32 v117, v67, v8
	v_fmac_f32_e32 v118, v66, v25
	v_fmac_f32_e32 v119, v67, v9
	v_fmac_f32_e32 v120, v66, v26
	v_fmac_f32_e32 v121, v67, v10
	v_fmac_f32_e32 v122, v66, v27
	v_fmac_f32_e32 v123, v67, v11
	v_fmac_f32_e32 v124, v66, v28
	v_fmac_f32_e32 v125, v67, v12
	v_fmac_f32_e32 v126, v66, v29
	v_fmac_f32_e32 v127, v67, v13
	v_fmac_f32_e32 v128, v66, v30
	v_fmac_f32_e32 v129, v67, v14
	v_fmac_f32_e32 v130, v66, v31
	v_fmac_f32_e32 v131, v67, v15
	s_add_u32 s14, s8, 0x21000
	s_addc_u32 s15, s9, 0
	global_store_dword v64, v100, s[14:15] offset:-4096 sc0 sc1
	global_store_dword v64, v101, s[14:15] offset:-3968 sc0 sc1
	global_store_dword v64, v102, s[14:15] sc0 sc1
	global_store_dword v64, v103, s[14:15] offset:128 sc0 sc1
	s_add_u32 s14, s8, 0x23000
	s_addc_u32 s15, s9, 0
	global_store_dword v64, v104, s[14:15] offset:-4096 sc0 sc1
	global_store_dword v64, v105, s[14:15] offset:-3968 sc0 sc1
	global_store_dword v64, v106, s[14:15] sc0 sc1
	global_store_dword v64, v107, s[14:15] offset:128 sc0 sc1
	s_add_u32 s14, s8, 0x29000
	s_addc_u32 s15, s9, 0
	global_store_dword v64, v108, s[14:15] offset:-4096 sc0 sc1
	global_store_dword v64, v109, s[14:15] offset:-3968 sc0 sc1
	global_store_dword v64, v110, s[14:15] sc0 sc1
	global_store_dword v64, v111, s[14:15] offset:128 sc0 sc1
	s_add_u32 s14, s8, 0x2b000
	s_addc_u32 s15, s9, 0
	global_store_dword v64, v112, s[14:15] offset:-4096 sc0 sc1
	global_store_dword v64, v113, s[14:15] offset:-3968 sc0 sc1
	global_store_dword v64, v114, s[14:15] sc0 sc1
	global_store_dword v64, v115, s[14:15] offset:128 sc0 sc1
	s_add_u32 s14, s8, 0x31000
	s_addc_u32 s15, s9, 0
	global_store_dword v64, v116, s[14:15] offset:-4096 sc0 sc1
	global_store_dword v64, v117, s[14:15] offset:-3968 sc0 sc1
	global_store_dword v64, v118, s[14:15] sc0 sc1
	global_store_dword v64, v119, s[14:15] offset:128 sc0 sc1
	s_add_u32 s14, s8, 0x33000
	s_addc_u32 s15, s9, 0
	global_store_dword v64, v120, s[14:15] offset:-4096 sc0 sc1
	global_store_dword v64, v121, s[14:15] offset:-3968 sc0 sc1
	global_store_dword v64, v122, s[14:15] sc0 sc1
	global_store_dword v64, v123, s[14:15] offset:128 sc0 sc1
	s_add_u32 s14, s8, 0x39000
	s_addc_u32 s15, s9, 0
	global_store_dword v64, v124, s[14:15] offset:-4096 sc0 sc1
	global_store_dword v64, v125, s[14:15] offset:-3968 sc0 sc1
	global_store_dword v64, v126, s[14:15] sc0 sc1
	global_store_dword v64, v127, s[14:15] offset:128 sc0 sc1
	s_add_u32 s14, s8, 0x3b000
	s_addc_u32 s15, s9, 0
	global_store_dword v64, v128, s[14:15] offset:-4096 sc0 sc1
	global_store_dword v64, v129, s[14:15] offset:-3968 sc0 sc1
	global_store_dword v64, v130, s[14:15] sc0 sc1
	global_store_dword v64, v131, s[14:15] offset:128 sc0 sc1
	s_branch .LBB0_1578

.LBB0_2253:
	s_waitcnt vmcnt(0)
	s_lshl_b32 s6, s5, 19
	s_lshl_b32 s7, s2, 9
	v_readfirstlane_b32 s2, v128
	v_readfirstlane_b32 s3, v129
	v_readlane_b32 s0, v255, 9
	s_add_u32 s8, s2, s56
	s_addc_u32 s9, s3, s57
	s_add_u32 s8, s8, s6
	s_addc_u32 s9, s9, 0
	s_add_u32 s8, s8, s7
	s_addc_u32 s9, s9, 0
	s_mov_b64 s[10:11], s[8:9]
	s_mul_i32 s12, s0, 0x12000
	s_add_u32 s12, s12, 0x2a25000
	s_sub_u32 s1, s5, 16
	s_lshr_b32 s1, s1, 4
	s_cmp_lt_u32 s5, 32
	s_cselect_b32 s1, 0, s1
	s_mul_i32 s1, s1, 0x6000
	s_add_u32 s12, s12, s1
	s_add_u32 s12, s12, s7
	s_add_u32 s12, s2, s12
	s_addc_u32 s13, s3, 0
	v_and_b32_e32 v64, 31, v231
	v_bfe_u32 v65, v231, 6, 1
	v_lshl_or_b32 v65, v65, 6, v64
	v_lshlrev_b32_e32 v65, 2, v65
	v_bfe_u32 v64, v231, 5, 1
	v_bfe_u32 v66, v231, 7, 1
	v_lshl_or_b32 v64, v66, 4, v64
	v_lshl_or_b32 v64, v64, 14, v65
	global_load_dword v66, v65, s[12:13]
	global_load_dword v67, v65, s[12:13] offset:128
	s_add_u32 s14, s10, 0x1000
	s_addc_u32 s15, s11, 0
	global_load_dword v68, v64, s[14:15] offset:-4096
	global_load_dword v69, v64, s[14:15] offset:-3968
	global_load_dword v70, v64, s[14:15]
	global_load_dword v71, v64, s[14:15] offset:128
	s_add_u32 s14, s10, 0x3000
	s_addc_u32 s15, s11, 0
	global_load_dword v72, v64, s[14:15] offset:-4096
	global_load_dword v73, v64, s[14:15] offset:-3968
	global_load_dword v74, v64, s[14:15]
	global_load_dword v75, v64, s[14:15] offset:128
	s_add_u32 s14, s10, 0x9000
	s_addc_u32 s15, s11, 0
	global_load_dword v76, v64, s[14:15] offset:-4096
	global_load_dword v77, v64, s[14:15] offset:-3968
	global_load_dword v78, v64, s[14:15]
	global_load_dword v79, v64, s[14:15] offset:128
	s_add_u32 s14, s10, 0xb000
	s_addc_u32 s15, s11, 0
	global_load_dword v80, v64, s[14:15] offset:-4096
	global_load_dword v81, v64, s[14:15] offset:-3968
	global_load_dword v82, v64, s[14:15]
	global_load_dword v83, v64, s[14:15] offset:128
	s_add_u32 s14, s10, 0x11000
	s_addc_u32 s15, s11, 0
	global_load_dword v84, v64, s[14:15] offset:-4096
	global_load_dword v85, v64, s[14:15] offset:-3968
	global_load_dword v86, v64, s[14:15]
	global_load_dword v87, v64, s[14:15] offset:128
	s_add_u32 s14, s10, 0x13000
	s_addc_u32 s15, s11, 0
	global_load_dword v88, v64, s[14:15] offset:-4096
	global_load_dword v89, v64, s[14:15] offset:-3968
	global_load_dword v90, v64, s[14:15]
	global_load_dword v91, v64, s[14:15] offset:128
	s_add_u32 s14, s10, 0x19000
	s_addc_u32 s15, s11, 0
	global_load_dword v92, v64, s[14:15] offset:-4096
	global_load_dword v93, v64, s[14:15] offset:-3968
	global_load_dword v94, v64, s[14:15]
	global_load_dword v95, v64, s[14:15] offset:128
	s_add_u32 s14, s10, 0x1b000
	s_addc_u32 s15, s11, 0
	global_load_dword v96, v64, s[14:15] offset:-4096
	global_load_dword v97, v64, s[14:15] offset:-3968
	global_load_dword v98, v64, s[14:15]
	global_load_dword v99, v64, s[14:15] offset:128
	s_add_u32 s14, s10, 0x21000
	s_addc_u32 s15, s11, 0
	global_load_dword v100, v64, s[14:15] offset:-4096
	global_load_dword v101, v64, s[14:15] offset:-3968
	global_load_dword v102, v64, s[14:15]
	global_load_dword v103, v64, s[14:15] offset:128
	s_add_u32 s14, s10, 0x23000
	s_addc_u32 s15, s11, 0
	global_load_dword v104, v64, s[14:15] offset:-4096
	global_load_dword v105, v64, s[14:15] offset:-3968
	global_load_dword v106, v64, s[14:15]
	global_load_dword v107, v64, s[14:15] offset:128
	s_add_u32 s14, s10, 0x29000
	s_addc_u32 s15, s11, 0
	global_load_dword v108, v64, s[14:15] offset:-4096
	global_load_dword v109, v64, s[14:15] offset:-3968
	global_load_dword v110, v64, s[14:15]
	global_load_dword v111, v64, s[14:15] offset:128
	s_add_u32 s14, s10, 0x2b000
	s_addc_u32 s15, s11, 0
	global_load_dword v112, v64, s[14:15] offset:-4096
	global_load_dword v113, v64, s[14:15] offset:-3968
	global_load_dword v114, v64, s[14:15]
	global_load_dword v115, v64, s[14:15] offset:128
	s_add_u32 s14, s10, 0x31000
	s_addc_u32 s15, s11, 0
	global_load_dword v116, v64, s[14:15] offset:-4096
	global_load_dword v117, v64, s[14:15] offset:-3968
	global_load_dword v118, v64, s[14:15]
	global_load_dword v119, v64, s[14:15] offset:128
	s_add_u32 s14, s10, 0x33000
	s_addc_u32 s15, s11, 0
	global_load_dword v120, v64, s[14:15] offset:-4096
	global_load_dword v121, v64, s[14:15] offset:-3968
	global_load_dword v122, v64, s[14:15]
	global_load_dword v123, v64, s[14:15] offset:128
	s_add_u32 s14, s10, 0x39000
	s_addc_u32 s15, s11, 0
	global_load_dword v124, v64, s[14:15] offset:-4096
	global_load_dword v125, v64, s[14:15] offset:-3968
	global_load_dword v126, v64, s[14:15]
	global_load_dword v127, v64, s[14:15] offset:128
	s_add_u32 s14, s10, 0x3b000
	s_addc_u32 s15, s11, 0
	global_load_dword v128, v64, s[14:15] offset:-4096
	global_load_dword v129, v64, s[14:15] offset:-3968
	global_load_dword v130, v64, s[14:15]
	global_load_dword v131, v64, s[14:15] offset:128
	s_waitcnt vmcnt(32)
	v_fmac_f32_e32 v68, v66, v48
	v_fmac_f32_e32 v69, v67, v32
	v_fmac_f32_e32 v70, v66, v49
	v_fmac_f32_e32 v71, v67, v33
	v_fmac_f32_e32 v72, v66, v50
	v_fmac_f32_e32 v73, v67, v34
	v_fmac_f32_e32 v74, v66, v51
	v_fmac_f32_e32 v75, v67, v35
	v_fmac_f32_e32 v76, v66, v52
	v_fmac_f32_e32 v77, v67, v36
	v_fmac_f32_e32 v78, v66, v53
	v_fmac_f32_e32 v79, v67, v37
	v_fmac_f32_e32 v80, v66, v54
	v_fmac_f32_e32 v81, v67, v38
	v_fmac_f32_e32 v82, v66, v55
	v_fmac_f32_e32 v83, v67, v39
	v_fmac_f32_e32 v84, v66, v56
	v_fmac_f32_e32 v85, v67, v40
	v_fmac_f32_e32 v86, v66, v57
	v_fmac_f32_e32 v87, v67, v41
	v_fmac_f32_e32 v88, v66, v58
	v_fmac_f32_e32 v89, v67, v42
	v_fmac_f32_e32 v90, v66, v59
	v_fmac_f32_e32 v91, v67, v43
	v_fmac_f32_e32 v92, v66, v60
	v_fmac_f32_e32 v93, v67, v44
	v_fmac_f32_e32 v94, v66, v61
	v_fmac_f32_e32 v95, v67, v45
	v_fmac_f32_e32 v96, v66, v62
	v_fmac_f32_e32 v97, v67, v46
	v_fmac_f32_e32 v98, v66, v63
	v_fmac_f32_e32 v99, v67, v47
	s_add_u32 s14, s8, 0x1000
	s_addc_u32 s15, s9, 0
	global_store_dword v64, v68, s[14:15] offset:-4096 sc0 sc1
	global_store_dword v64, v69, s[14:15] offset:-3968 sc0 sc1
	global_store_dword v64, v70, s[14:15] sc0 sc1
	global_store_dword v64, v71, s[14:15] offset:128 sc0 sc1
	s_add_u32 s14, s8, 0x3000
	s_addc_u32 s15, s9, 0
	global_store_dword v64, v72, s[14:15] offset:-4096 sc0 sc1
	global_store_dword v64, v73, s[14:15] offset:-3968 sc0 sc1
	global_store_dword v64, v74, s[14:15] sc0 sc1
	global_store_dword v64, v75, s[14:15] offset:128 sc0 sc1
	s_add_u32 s14, s8, 0x9000
	s_addc_u32 s15, s9, 0
	global_store_dword v64, v76, s[14:15] offset:-4096 sc0 sc1
	global_store_dword v64, v77, s[14:15] offset:-3968 sc0 sc1
	global_store_dword v64, v78, s[14:15] sc0 sc1
	global_store_dword v64, v79, s[14:15] offset:128 sc0 sc1
	s_add_u32 s14, s8, 0xb000
	s_addc_u32 s15, s9, 0
	global_store_dword v64, v80, s[14:15] offset:-4096 sc0 sc1
	global_store_dword v64, v81, s[14:15] offset:-3968 sc0 sc1
	global_store_dword v64, v82, s[14:15] sc0 sc1
	global_store_dword v64, v83, s[14:15] offset:128 sc0 sc1
	s_add_u32 s14, s8, 0x11000
	s_addc_u32 s15, s9, 0
	global_store_dword v64, v84, s[14:15] offset:-4096 sc0 sc1
	global_store_dword v64, v85, s[14:15] offset:-3968 sc0 sc1
	global_store_dword v64, v86, s[14:15] sc0 sc1
	global_store_dword v64, v87, s[14:15] offset:128 sc0 sc1
	s_add_u32 s14, s8, 0x13000
	s_addc_u32 s15, s9, 0
	global_store_dword v64, v88, s[14:15] offset:-4096 sc0 sc1
	global_store_dword v64, v89, s[14:15] offset:-3968 sc0 sc1
	global_store_dword v64, v90, s[14:15] sc0 sc1
	global_store_dword v64, v91, s[14:15] offset:128 sc0 sc1
	s_add_u32 s14, s8, 0x19000
	s_addc_u32 s15, s9, 0
	global_store_dword v64, v92, s[14:15] offset:-4096 sc0 sc1
	global_store_dword v64, v93, s[14:15] offset:-3968 sc0 sc1
	global_store_dword v64, v94, s[14:15] sc0 sc1
	global_store_dword v64, v95, s[14:15] offset:128 sc0 sc1
	s_add_u32 s14, s8, 0x1b000
	s_addc_u32 s15, s9, 0
	global_store_dword v64, v96, s[14:15] offset:-4096 sc0 sc1
	global_store_dword v64, v97, s[14:15] offset:-3968 sc0 sc1
	global_store_dword v64, v98, s[14:15] sc0 sc1
	global_store_dword v64, v99, s[14:15] offset:128 sc0 sc1
	s_waitcnt vmcnt(32)
	v_fmac_f32_e32 v100, v66, v16
	v_fmac_f32_e32 v101, v67, v0
	v_fmac_f32_e32 v102, v66, v17
	v_fmac_f32_e32 v103, v67, v1
	v_fmac_f32_e32 v104, v66, v18
	v_fmac_f32_e32 v105, v67, v2
	v_fmac_f32_e32 v106, v66, v19
	v_fmac_f32_e32 v107, v67, v3
	v_fmac_f32_e32 v108, v66, v20
	v_fmac_f32_e32 v109, v67, v4
	v_fmac_f32_e32 v110, v66, v21
	v_fmac_f32_e32 v111, v67, v5
	v_fmac_f32_e32 v112, v66, v22
	v_fmac_f32_e32 v113, v67, v6
	v_fmac_f32_e32 v114, v66, v23
	v_fmac_f32_e32 v115, v67, v7
	v_fmac_f32_e32 v116, v66, v24
	v_fmac_f32_e32 v117, v67, v8
	v_fmac_f32_e32 v118, v66, v25
	v_fmac_f32_e32 v119, v67, v9
	v_fmac_f32_e32 v120, v66, v26
	v_fmac_f32_e32 v121, v67, v10
	v_fmac_f32_e32 v122, v66, v27
	v_fmac_f32_e32 v123, v67, v11
	v_fmac_f32_e32 v124, v66, v28
	v_fmac_f32_e32 v125, v67, v12
	v_fmac_f32_e32 v126, v66, v29
	v_fmac_f32_e32 v127, v67, v13
	v_fmac_f32_e32 v128, v66, v30
	v_fmac_f32_e32 v129, v67, v14
	v_fmac_f32_e32 v130, v66, v31
	v_fmac_f32_e32 v131, v67, v15
	s_add_u32 s14, s8, 0x21000
	s_addc_u32 s15, s9, 0
	global_store_dword v64, v100, s[14:15] offset:-4096 sc0 sc1
	global_store_dword v64, v101, s[14:15] offset:-3968 sc0 sc1
	global_store_dword v64, v102, s[14:15] sc0 sc1
	global_store_dword v64, v103, s[14:15] offset:128 sc0 sc1
	s_add_u32 s14, s8, 0x23000
	s_addc_u32 s15, s9, 0
	global_store_dword v64, v104, s[14:15] offset:-4096 sc0 sc1
	global_store_dword v64, v105, s[14:15] offset:-3968 sc0 sc1
	global_store_dword v64, v106, s[14:15] sc0 sc1
	global_store_dword v64, v107, s[14:15] offset:128 sc0 sc1
	s_add_u32 s14, s8, 0x29000
	s_addc_u32 s15, s9, 0
	global_store_dword v64, v108, s[14:15] offset:-4096 sc0 sc1
	global_store_dword v64, v109, s[14:15] offset:-3968 sc0 sc1
	global_store_dword v64, v110, s[14:15] sc0 sc1
	global_store_dword v64, v111, s[14:15] offset:128 sc0 sc1
	s_add_u32 s14, s8, 0x2b000
	s_addc_u32 s15, s9, 0
	global_store_dword v64, v112, s[14:15] offset:-4096 sc0 sc1
	global_store_dword v64, v113, s[14:15] offset:-3968 sc0 sc1
	global_store_dword v64, v114, s[14:15] sc0 sc1
	global_store_dword v64, v115, s[14:15] offset:128 sc0 sc1
	s_add_u32 s14, s8, 0x31000
	s_addc_u32 s15, s9, 0
	global_store_dword v64, v116, s[14:15] offset:-4096 sc0 sc1
	global_store_dword v64, v117, s[14:15] offset:-3968 sc0 sc1
	global_store_dword v64, v118, s[14:15] sc0 sc1
	global_store_dword v64, v119, s[14:15] offset:128 sc0 sc1
	s_add_u32 s14, s8, 0x33000
	s_addc_u32 s15, s9, 0
	global_store_dword v64, v120, s[14:15] offset:-4096 sc0 sc1
	global_store_dword v64, v121, s[14:15] offset:-3968 sc0 sc1
	global_store_dword v64, v122, s[14:15] sc0 sc1
	global_store_dword v64, v123, s[14:15] offset:128 sc0 sc1
	s_add_u32 s14, s8, 0x39000
	s_addc_u32 s15, s9, 0
	global_store_dword v64, v124, s[14:15] offset:-4096 sc0 sc1
	global_store_dword v64, v125, s[14:15] offset:-3968 sc0 sc1
	global_store_dword v64, v126, s[14:15] sc0 sc1
	global_store_dword v64, v127, s[14:15] offset:128 sc0 sc1
	s_add_u32 s14, s8, 0x3b000
	s_addc_u32 s15, s9, 0
	global_store_dword v64, v128, s[14:15] offset:-4096 sc0 sc1
	global_store_dword v64, v129, s[14:15] offset:-3968 sc0 sc1
	global_store_dword v64, v130, s[14:15] sc0 sc1
	global_store_dword v64, v131, s[14:15] offset:128 sc0 sc1
	s_add_i32 s4, s4, 1
	s_mov_b64 s[2:3], 0
	s_barrier

.LBB0_2262:
	s_mov_b64 s[2:3], -1
	s_and_b64 vcc, exec, s[0:1]
	s_cbranch_vccz .LBB0_2254
	s_ashr_i32 s0, s6, 31
	ds_read_b64 v[128:129], v229 offset:63760
	ds_read_b64 v[130:131], v229 offset:63760
	ds_read_b64 v[0:1], v229 offset:63760
	s_lshr_b32 s0, s0, 29
	s_add_i32 s0, s6, s0
	s_and_b32 s0, s0, -8
	ds_read_b64 v[2:3], v229 offset:63760
	s_sub_i32 s2, s6, s0
	s_mul_hi_i32 s1, s5, 0xb0000
	s_mul_i32 s0, s5, 0xb0000
	s_waitcnt lgkmcnt(0)
	v_lshl_add_u64 v[4:5], v[0:1], 0, s[0:1]
	s_mov_b64 s[0:1], 0xb2d4000
	v_lshl_add_u64 v[4:5], v[4:5], 0, s[0:1]
	s_mul_i32 s0, s2, 0xb0000
	s_ashr_i32 s1, s0, 31
	v_lshl_add_u64 v[2:3], v[2:3], 0, s[0:1]
	v_mov_b32_e32 v14, v231
	v_lshl_add_u64 v[6:7], v[2:3], 0, s[54:55]
	s_movk_i32 s3, 0x90
	v_ashrrev_i32_e32 v15, 3, v14
	v_lshlrev_b32_e32 v8, 4, v14
	v_and_b32_e32 v228, 0x70, v8
	v_mad_i64_i32 v[6:7], s[0:1], v15, s46, v[6:7]
	v_lshl_add_u64 v[6:7], v[6:7], 0, v[228:229]
	v_mad_u64_u32 v[132:133], s[0:1], v15, s3, v[228:229]
	v_ashrrev_i32_e32 v8, 1, v14
	v_and_b32_e32 v133, 0xffffffc0, v8
	v_add_co_u32_e32 v8, vcc, s47, v6
	v_mad_i64_i32 v[4:5], s[0:1], v15, s46, v[4:5]
	s_nop 0
	v_addc_co_u32_e32 v9, vcc, 0, v7, vcc
	v_add_co_u32_e32 v10, vcc, s48, v6
	v_lshl_add_u64 v[4:5], v[4:5], 0, v[228:229]
	s_nop 0
	v_addc_co_u32_e32 v11, vcc, 0, v7, vcc
	v_add_co_u32_e32 v12, vcc, s49, v6
	v_bfe_u32 v140, v14, 5, 1
	s_nop 0
	v_addc_co_u32_e32 v13, vcc, 0, v7, vcc
	global_load_dwordx4 v[88:91], v[10:11], off
	global_load_dwordx4 v[84:87], v[12:13], off
	global_load_dwordx4 v[92:95], v[8:9], off
	global_load_dwordx4 v[80:83], v[6:7], off
	v_add_co_u32_e32 v6, vcc, s47, v4
	v_and_or_b32 v16, v14, 31, v133
	s_nop 0
	v_addc_co_u32_e32 v7, vcc, 0, v5, vcc
	v_add_co_u32_e32 v8, vcc, s48, v4
	s_nop 1
	v_addc_co_u32_e32 v9, vcc, 0, v5, vcc
	global_load_dwordx4 v[72:75], v[6:7], off
	global_load_dwordx4 v[76:79], v[8:9], off
	v_add_co_u32_e32 v6, vcc, s49, v4
	s_nop 1
	v_addc_co_u32_e32 v7, vcc, 0, v5, vcc
	global_load_dwordx4 v[68:71], v[6:7], off
	global_load_dwordx4 v[64:67], v[4:5], off
	v_lshlrev_b32_e32 v4, 4, v140
	v_mad_u64_u32 v[134:135], s[0:1], v16, s3, v[4:5]
	v_and_b32_e32 v135, 0x5f, v14
	v_mad_u32_u24 v141, v135, s3, v4
	v_mad_i64_i32 v[4:5], s[0:1], v15, s46, 0
	v_and_b32_e32 v6, 7, v14
	v_lshl_or_b32 v4, v6, 4, v4
	v_lshl_add_u64 v[136:137], v[2:3], 0, v[4:5]
	v_mad_i64_i32 v[2:3], s[0:1], s5, v251, v[4:5]
	v_lshl_add_u64 v[138:139], v[0:1], 0, v[2:3]
	v_mov_b32_e32 v0, 0
	s_mov_b32 s3, 0
	s_mov_b64 s[0:1], 0
	v_mov_b32_e32 v1, v0
	v_mov_b32_e32 v2, v0
	v_mov_b32_e32 v3, v0
	v_mov_b32_e32 v4, v0
	v_mov_b32_e32 v5, v0
	v_mov_b32_e32 v6, v0
	v_mov_b32_e32 v7, v0
	v_mov_b32_e32 v8, v0
	v_mov_b32_e32 v9, v0
	v_mov_b32_e32 v10, v0
	v_mov_b32_e32 v11, v0
	v_mov_b32_e32 v12, v0
	v_mov_b32_e32 v13, v0
	v_mov_b32_e32 v14, v0
	v_mov_b32_e32 v15, v0
	v_mov_b32_e32 v16, v0
	v_mov_b32_e32 v17, v0
	v_mov_b32_e32 v18, v0
	v_mov_b32_e32 v19, v0
	v_mov_b32_e32 v20, v0
	v_mov_b32_e32 v21, v0
	v_mov_b32_e32 v22, v0
	v_mov_b32_e32 v23, v0
	v_mov_b32_e32 v24, v0
	v_mov_b32_e32 v25, v0
	v_mov_b32_e32 v26, v0
	v_mov_b32_e32 v27, v0
	v_mov_b32_e32 v28, v0
	v_mov_b32_e32 v29, v0
	v_mov_b32_e32 v30, v0
	v_mov_b32_e32 v31, v0
	v_mov_b32_e32 v32, v0
	v_mov_b32_e32 v33, v0
	v_mov_b32_e32 v34, v0
	v_mov_b32_e32 v35, v0
	v_mov_b32_e32 v36, v0
	v_mov_b32_e32 v37, v0
	v_mov_b32_e32 v38, v0
	v_mov_b32_e32 v39, v0
	v_mov_b32_e32 v40, v0
	v_mov_b32_e32 v41, v0
	v_mov_b32_e32 v42, v0
	v_mov_b32_e32 v43, v0
	v_mov_b32_e32 v44, v0
	v_mov_b32_e32 v45, v0
	v_mov_b32_e32 v46, v0
	v_mov_b32_e32 v47, v0
	v_mov_b32_e32 v48, v0
	v_mov_b32_e32 v49, v0
	v_mov_b32_e32 v50, v0
	v_mov_b32_e32 v51, v0
	v_mov_b32_e32 v52, v0
	v_mov_b32_e32 v53, v0
	v_mov_b32_e32 v54, v0
	v_mov_b32_e32 v55, v0
	v_mov_b32_e32 v56, v0
	v_mov_b32_e32 v57, v0
	v_mov_b32_e32 v58, v0
	v_mov_b32_e32 v59, v0
	v_mov_b32_e32 v60, v0
	v_mov_b32_e32 v61, v0
	v_mov_b32_e32 v62, v0
	v_mov_b32_e32 v63, v0
	v_lshl_add_u64 v[168:169], v[138:139], 0, s[0:1]
	v_add_co_u32_e32 v160, vcc, 0xb2d4000, v168
	v_lshl_add_u64 v[184:185], v[136:137], 0, s[0:1]
	s_nop 0
	v_addc_co_u32_e32 v161, vcc, 0, v169, vcc
	v_add_co_u32_e32 v164, vcc, 0xb300000, v168
	s_nop 1
	v_addc_co_u32_e32 v165, vcc, 0, v169, vcc
	v_add_co_u32_e32 v170, vcc, 0xb32c000, v168
	global_load_dwordx4 v[160:163], v[160:161], off offset:128
	s_nop 0
	global_load_dwordx4 v[164:167], v[164:165], off offset:128
	v_addc_co_u32_e32 v171, vcc, 0, v169, vcc
	v_add_co_u32_e32 v168, vcc, 0xb358000, v168
	s_nop 1
	v_addc_co_u32_e32 v169, vcc, 0, v169, vcc
	v_add_co_u32_e32 v176, vcc, 0x1200000, v184
	global_load_dwordx4 v[172:175], v[170:171], off offset:128
	s_nop 0
	global_load_dwordx4 v[168:171], v[168:169], off offset:128
	v_addc_co_u32_e32 v177, vcc, 0, v185, vcc
	v_add_co_u32_e32 v180, vcc, 0x122c000, v184
	s_nop 1
	v_addc_co_u32_e32 v181, vcc, 0, v185, vcc
	v_add_co_u32_e32 v186, vcc, 0x1258000, v184
	global_load_dwordx4 v[176:179], v[176:177], off offset:128
	s_nop 0
	global_load_dwordx4 v[180:183], v[180:181], off offset:128
	v_addc_co_u32_e32 v187, vcc, 0, v185, vcc
	v_add_co_u32_e32 v188, vcc, 0x1284000, v184
	s_nop 1
	v_addc_co_u32_e32 v189, vcc, 0, v185, vcc
	global_load_dwordx4 v[184:187], v[186:187], off offset:128
	s_nop 0
	global_load_dwordx4 v[188:191], v[188:189], off offset:128
	s_branch .Lgd_even
.Lgd_even:
	s_waitcnt vmcnt(63) expcnt(7) lgkmcnt(15)
	s_barrier
	s_waitcnt vmcnt(8)
	ds_write_b128 v132, v[64:67]
	ds_write_b128 v132, v[68:71] offset:4608
	ds_write_b128 v132, v[76:79] offset:9216
	ds_write_b128 v132, v[72:75] offset:13824
	ds_write_b128 v132, v[80:83] offset:18432
	ds_write_b128 v132, v[84:87] offset:23040
	ds_write_b128 v132, v[88:91] offset:27648
	ds_write_b128 v132, v[92:95] offset:32256
	s_waitcnt lgkmcnt(0)
	s_barrier
	ds_read_b128 v[112:115], v134
	ds_read_b128 v[96:99], v134 offset:32
	ds_read_b128 v[120:123], v141 offset:18432
	ds_read_b128 v[100:103], v141 offset:18464
	ds_read_b128 v[116:119], v134 offset:4608
	ds_read_b128 v[104:107], v134 offset:4640
	ds_read_b128 v[124:127], v141 offset:23040
	ds_read_b128 v[108:111], v141 offset:23072
	s_cmp_ge_u32 s0, 0x1500
	s_cbranch_scc1 .Lgd_even_mf
	v_lshl_add_u64 v[72:73], v[138:139], 0, s[0:1]
	v_add_co_u32_e32 v64, vcc, 0xb2d4000, v72
	v_lshl_add_u64 v[88:89], v[136:137], 0, s[0:1]
	s_nop 0
	v_addc_co_u32_e32 v65, vcc, 0, v73, vcc
	v_add_co_u32_e32 v68, vcc, 0xb300000, v72
	s_nop 1
	v_addc_co_u32_e32 v69, vcc, 0, v73, vcc
	v_add_co_u32_e32 v74, vcc, 0xb32c000, v72
	global_load_dwordx4 v[64:67], v[64:65], off offset:256
	s_nop 0
	global_load_dwordx4 v[68:71], v[68:69], off offset:256
	v_addc_co_u32_e32 v75, vcc, 0, v73, vcc
	v_add_co_u32_e32 v72, vcc, 0xb358000, v72
	s_nop 1
	v_addc_co_u32_e32 v73, vcc, 0, v73, vcc
	v_add_co_u32_e32 v80, vcc, 0x1200000, v88
	global_load_dwordx4 v[76:79], v[74:75], off offset:256
	s_nop 0
	global_load_dwordx4 v[72:75], v[72:73], off offset:256
	v_addc_co_u32_e32 v81, vcc, 0, v89, vcc
	v_add_co_u32_e32 v84, vcc, 0x122c000, v88
	s_nop 1
	v_addc_co_u32_e32 v85, vcc, 0, v89, vcc
	v_add_co_u32_e32 v90, vcc, 0x1258000, v88
	global_load_dwordx4 v[80:83], v[80:81], off offset:256
	s_nop 0
	global_load_dwordx4 v[84:87], v[84:85], off offset:256
	v_addc_co_u32_e32 v91, vcc, 0, v89, vcc
	v_add_co_u32_e32 v92, vcc, 0x1284000, v88
	s_nop 1
	v_addc_co_u32_e32 v93, vcc, 0, v89, vcc
	global_load_dwordx4 v[88:91], v[90:91], off offset:256
	s_nop 0
	global_load_dwordx4 v[92:95], v[92:93], off offset:256
.Lgd_even_mf:
	s_waitcnt lgkmcnt(5)
	v_mfma_f32_32x32x16_bf16 v[48:63], v[112:115], v[120:123], v[48:63]
	s_waitcnt lgkmcnt(1)
	v_mfma_f32_32x32x16_bf16 v[32:47], v[112:115], v[124:127], v[32:47]
	v_mfma_f32_32x32x16_bf16 v[16:31], v[116:119], v[120:123], v[16:31]
	v_mfma_f32_32x32x16_bf16 v[0:15], v[116:119], v[124:127], v[0:15]
	ds_read_b128 v[112:115], v134 offset:64
	ds_read_b128 v[116:119], v134 offset:4672
	ds_read_b128 v[120:123], v141 offset:18496
	ds_read_b128 v[124:127], v141 offset:23104
	v_mfma_f32_32x32x16_bf16 v[48:63], v[96:99], v[100:103], v[48:63]
	s_waitcnt lgkmcnt(4)
	v_mfma_f32_32x32x16_bf16 v[32:47], v[96:99], v[108:111], v[32:47]
	v_mfma_f32_32x32x16_bf16 v[16:31], v[104:107], v[100:103], v[16:31]
	v_mfma_f32_32x32x16_bf16 v[0:15], v[104:107], v[108:111], v[0:15]
	ds_read_b128 v[96:99], v134 offset:96
	ds_read_b128 v[100:103], v134 offset:4704
	ds_read_b128 v[104:107], v141 offset:18528
	ds_read_b128 v[108:111], v141 offset:23136
	s_waitcnt lgkmcnt(5)
	v_mfma_f32_32x32x16_bf16 v[48:63], v[112:115], v[120:123], v[48:63]
	s_waitcnt lgkmcnt(4)
	v_mfma_f32_32x32x16_bf16 v[32:47], v[112:115], v[124:127], v[32:47]
	v_mfma_f32_32x32x16_bf16 v[16:31], v[116:119], v[120:123], v[16:31]
	v_mfma_f32_32x32x16_bf16 v[0:15], v[116:119], v[124:127], v[0:15]
	s_waitcnt lgkmcnt(1)
	v_mfma_f32_32x32x16_bf16 v[48:63], v[96:99], v[104:107], v[48:63]
	s_waitcnt lgkmcnt(0)
	v_mfma_f32_32x32x16_bf16 v[32:47], v[96:99], v[108:111], v[32:47]
	v_mfma_f32_32x32x16_bf16 v[16:31], v[100:103], v[104:107], v[16:31]
	v_mfma_f32_32x32x16_bf16 v[0:15], v[100:103], v[108:111], v[0:15]
	s_add_u32 s0, s0, 0x80
	s_addc_u32 s1, s1, 0
	s_add_i32 s3, s3, 1
	s_waitcnt vmcnt(63) expcnt(7) lgkmcnt(15)
	s_barrier
	s_cmp_ge_u32 s0, 0x1580
	s_cbranch_scc1 .Lgd_odd_last
	s_waitcnt vmcnt(8)
	s_branch .Lgd_odd_w

.Lgd_odd_w:
	ds_write_b128 v132, v[160:163]
	ds_write_b128 v132, v[164:167] offset:4608
	ds_write_b128 v132, v[172:175] offset:9216
	ds_write_b128 v132, v[168:171] offset:13824
	ds_write_b128 v132, v[176:179] offset:18432
	ds_write_b128 v132, v[180:183] offset:23040
	ds_write_b128 v132, v[184:187] offset:27648
	ds_write_b128 v132, v[188:191] offset:32256
	s_waitcnt lgkmcnt(0)
	s_barrier
	ds_read_b128 v[112:115], v134
	ds_read_b128 v[96:99], v134 offset:32
	ds_read_b128 v[120:123], v141 offset:18432
	ds_read_b128 v[100:103], v141 offset:18464
	ds_read_b128 v[116:119], v134 offset:4608
	ds_read_b128 v[104:107], v134 offset:4640
	ds_read_b128 v[124:127], v141 offset:23040
	ds_read_b128 v[108:111], v141 offset:23072
	s_cmp_ge_u32 s0, 0x1500
	s_cbranch_scc1 .Lgd_odd_mf
	v_lshl_add_u64 v[168:169], v[138:139], 0, s[0:1]
	v_add_co_u32_e32 v160, vcc, 0xb2d4000, v168
	v_lshl_add_u64 v[184:185], v[136:137], 0, s[0:1]
	s_nop 0
	v_addc_co_u32_e32 v161, vcc, 0, v169, vcc
	v_add_co_u32_e32 v164, vcc, 0xb300000, v168
	s_nop 1
	v_addc_co_u32_e32 v165, vcc, 0, v169, vcc
	v_add_co_u32_e32 v170, vcc, 0xb32c000, v168
	global_load_dwordx4 v[160:163], v[160:161], off offset:256
	s_nop 0
	global_load_dwordx4 v[164:167], v[164:165], off offset:256
	v_addc_co_u32_e32 v171, vcc, 0, v169, vcc
	v_add_co_u32_e32 v168, vcc, 0xb358000, v168
	s_nop 1
	v_addc_co_u32_e32 v169, vcc, 0, v169, vcc
	v_add_co_u32_e32 v176, vcc, 0x1200000, v184
	global_load_dwordx4 v[172:175], v[170:171], off offset:256
	s_nop 0
	global_load_dwordx4 v[168:171], v[168:169], off offset:256
	v_addc_co_u32_e32 v177, vcc, 0, v185, vcc
	v_add_co_u32_e32 v180, vcc, 0x122c000, v184
	s_nop 1
	v_addc_co_u32_e32 v181, vcc, 0, v185, vcc
	v_add_co_u32_e32 v186, vcc, 0x1258000, v184
	global_load_dwordx4 v[176:179], v[176:177], off offset:256
	s_nop 0
	global_load_dwordx4 v[180:183], v[180:181], off offset:256
	v_addc_co_u32_e32 v187, vcc, 0, v185, vcc
	v_add_co_u32_e32 v188, vcc, 0x1284000, v184
	s_nop 1
	v_addc_co_u32_e32 v189, vcc, 0, v185, vcc
	global_load_dwordx4 v[184:187], v[186:187], off offset:256
	s_nop 0
	global_load_dwordx4 v[188:191], v[188:189], off offset:256
.Lgd_odd_mf:
	s_waitcnt lgkmcnt(5)
	v_mfma_f32_32x32x16_bf16 v[48:63], v[112:115], v[120:123], v[48:63]
	s_waitcnt lgkmcnt(1)
	v_mfma_f32_32x32x16_bf16 v[32:47], v[112:115], v[124:127], v[32:47]
	v_mfma_f32_32x32x16_bf16 v[16:31], v[116:119], v[120:123], v[16:31]
	v_mfma_f32_32x32x16_bf16 v[0:15], v[116:119], v[124:127], v[0:15]
	ds_read_b128 v[112:115], v134 offset:64
	ds_read_b128 v[116:119], v134 offset:4672
	ds_read_b128 v[120:123], v141 offset:18496
	ds_read_b128 v[124:127], v141 offset:23104
	v_mfma_f32_32x32x16_bf16 v[48:63], v[96:99], v[100:103], v[48:63]
	s_waitcnt lgkmcnt(4)
	v_mfma_f32_32x32x16_bf16 v[32:47], v[96:99], v[108:111], v[32:47]
	v_mfma_f32_32x32x16_bf16 v[16:31], v[104:107], v[100:103], v[16:31]
	v_mfma_f32_32x32x16_bf16 v[0:15], v[104:107], v[108:111], v[0:15]
	ds_read_b128 v[96:99], v134 offset:96
	ds_read_b128 v[100:103], v134 offset:4704
	ds_read_b128 v[104:107], v141 offset:18528
	ds_read_b128 v[108:111], v141 offset:23136
	s_waitcnt lgkmcnt(5)
	v_mfma_f32_32x32x16_bf16 v[48:63], v[112:115], v[120:123], v[48:63]
	s_waitcnt lgkmcnt(4)
	v_mfma_f32_32x32x16_bf16 v[32:47], v[112:115], v[124:127], v[32:47]
	v_mfma_f32_32x32x16_bf16 v[16:31], v[116:119], v[120:123], v[16:31]
	v_mfma_f32_32x32x16_bf16 v[0:15], v[116:119], v[124:127], v[0:15]
	s_waitcnt lgkmcnt(1)
	v_mfma_f32_32x32x16_bf16 v[48:63], v[96:99], v[104:107], v[48:63]
	s_waitcnt lgkmcnt(0)
	v_mfma_f32_32x32x16_bf16 v[32:47], v[96:99], v[108:111], v[32:47]
	v_mfma_f32_32x32x16_bf16 v[16:31], v[100:103], v[104:107], v[16:31]
	v_mfma_f32_32x32x16_bf16 v[0:15], v[100:103], v[108:111], v[0:15]
	s_add_u32 s0, s0, 0x80
	s_addc_u32 s1, s1, 0
	s_add_i32 s3, s3, 1
	s_cmp_eq_u32 s0, 0x1600
	s_cbranch_scc1 .LBB0_2253
	s_branch .Lgd_even
